# attention item prologue: k-mean loads batched, first K/V tile loads hoisted above the gate computation (test)
# baseline (speedup 1.0000x reference)
; __device__ void attn_item(const Params& p, char* lds, int bh, int qi) {
;     ...
;   __syncthreads();
;   for (int i = tid; i < 16 * 64; i += NT) km[i] = p.kmean[(size_t)bh * 16 * 64 + i];
;   const int qpos = qi * 256 + wave * 32 + l31;
;   bf16x8 qf[4];
; #pragma unroll
;   for (int ks = 0; ks < 4; ++ks) qf[ks] = *(const bf16x8*)(Qg + (size_t)qpos * 64 + ks * 16 + 8 * h);
;   __syncthreads();
;   unsigned selmask = 0;
;   if (qi <= 3) selmask = (1u << qi) - 1u;
;     ...
;   auto gload = [&](int s) {
;     const int jb = qi - (s >> 2), sub = s & 3, key0 = jb * 256 + sub * 64;
;     rk = *(const u32x4*)(Kg + (size_t)(key0 + skey) * 64 + sch * 8);
;     rv = *(const u32x4*)(Vg + (size_t)skey * SEQ + key0 + sch * 8);
;   };
.LBB0_398:
	s_or_b64 exec, exec, s[4:5]
	s_waitcnt lgkmcnt(0)
	s_barrier
	ds_read_b32 v2, v124
	s_mov_b64 s[4:5], -1
	s_waitcnt lgkmcnt(0)
	v_cmp_lt_i32_e32 vcc, s31, v2
	v_readfirstlane_b32 s14, v2
	s_cbranch_vccnz .LBB0_393
	s_lshl_b32 s4, s14, 3
	s_and_b32 s36, s4, 56
	s_or_b32 s22, s36, s71
	s_lshl_b32 s6, s22, 12
	v_lshl_add_u64 v[2:3], v[102:103], 0, s[6:7]
	s_mov_b64 s[4:5], 0
	s_barrier
	global_load_dword v6, v[2:3], off
	global_load_dword v7, v[2:3], off offset:2048
	s_ashr_i32 s4, s14, 3
	s_sub_i32 s37, 15, s4
	s_lshl_b32 s6, s22, 19
	s_add_u32 s14, s8, s6
	s_addc_u32 s15, s9, 0
	s_lshl_b32 s4, s37, 8
	v_add_u32_e32 v94, s4, v113
	v_lshlrev_b64 v[2:3], 7, v[94:95]
	v_lshl_add_u64 v[2:3], s[14:15], 0, v[2:3]
	v_mov_b32_e32 v105, v95
	v_lshl_add_u64 v[2:3], v[2:3], 0, v[104:105]
	global_load_dwordx4 v[66:69], v[2:3], off
	global_load_dwordx4 v[70:73], v[2:3], off offset:32
	global_load_dwordx4 v[74:77], v[2:3], off offset:64
	global_load_dwordx4 v[78:81], v[2:3], off offset:96
	s_lshl_b32 s38, s22, 19
	s_add_u32 s38, s10, s38
	s_addc_u32 s39, s11, 0
	v_or_b32_e32 v176, s4, v240
	v_mov_b32_e32 v177, 0
	v_lshlrev_b64 v[176:177], 7, v[176:177]
	v_lshl_add_u64 v[176:177], s[38:39], 0, v[176:177]
	v_mov_b32_e32 v180, v106
	v_mov_b32_e32 v181, 0
	v_lshl_add_u64 v[176:177], v[176:177], 0, v[180:181]
	v_lshl_add_u64 v[178:179], v[96:97], 0, s[6:7]
	s_mov_b32 s38, s4
	s_mov_b32 s39, 0
	v_lshl_add_u64 v[178:179], s[38:39], 1, v[178:179]
	v_lshl_add_u64 v[178:179], v[178:179], 0, v[180:181]
	global_load_dwordx4 v[86:89], v[178:179], off
	global_load_dwordx4 v[82:85], v[176:177], off
	s_waitcnt vmcnt(7)
	ds_write_b32 v121, v6
	s_waitcnt vmcnt(6)
	ds_write_b32 v121, v7 offset:2048
	s_cmp_gt_u32 s37, 3
	s_mov_b64 s[14:15], -1
	s_waitcnt lgkmcnt(0)
	s_barrier
	s_cbranch_scc0 .LBB0_412
	v_cmp_lt_i32_e32 vcc, v156, v157
	v_mov_b32_e32 v34, 0
	s_waitcnt vmcnt(5)
	v_lshlrev_b32_e32 v15, 16, v66
	v_cndmask_b32_e32 v2, v1, v156, vcc
	v_lshlrev_b32_e32 v14, 2, v2
	v_lshlrev_b32_e32 v16, 16, v68
	v_and_b32_e32 v17, 0xffff0000, v66
	v_and_b32_e32 v18, 0xffff0000, v68
	v_lshlrev_b32_e32 v19, 16, v67
	v_lshlrev_b32_e32 v20, 16, v69
	v_and_b32_e32 v21, 0xffff0000, v67
	v_and_b32_e32 v22, 0xffff0000, v69
	s_waitcnt vmcnt(4)
	v_lshlrev_b32_e32 v23, 16, v70
	v_lshlrev_b32_e32 v24, 16, v72
	v_and_b32_e32 v25, 0xffff0000, v70
	v_and_b32_e32 v26, 0xffff0000, v72
	v_lshlrev_b32_e32 v27, 16, v71
	v_lshlrev_b32_e32 v28, 16, v73
	v_and_b32_e32 v29, 0xffff0000, v71
	v_and_b32_e32 v30, 0xffff0000, v73
	s_waitcnt vmcnt(3)
	v_lshlrev_b32_e32 v31, 16, v74
	v_lshlrev_b32_e32 v32, 16, v76
	v_and_b32_e32 v33, 0xffff0000, v74
	v_and_b32_e32 v35, 0xffff0000, v76
	v_lshlrev_b32_e32 v3, 16, v75
	v_lshlrev_b32_e32 v2, 16, v77
	v_and_b32_e32 v5, 0xffff0000, v75
	v_and_b32_e32 v4, 0xffff0000, v77
	s_waitcnt vmcnt(2)
	v_lshlrev_b32_e32 v7, 16, v78
	v_lshlrev_b32_e32 v6, 16, v80
	v_and_b32_e32 v9, 0xffff0000, v78
	v_and_b32_e32 v8, 0xffff0000, v80
	v_lshlrev_b32_e32 v11, 16, v79
	v_lshlrev_b32_e32 v10, 16, v81
	v_and_b32_e32 v13, 0xffff0000, v79
	v_and_b32_e32 v12, 0xffff0000, v81
	v_mov_b32_e32 v37, 0xff800000
	s_mov_b32 s5, 0
	v_mov_b32_e32 v36, v123
	v_mov_b32_e32 v38, 0xff800000
	v_mov_b32_e32 v41, 0xff800000
	v_mov_b32_e32 v39, 0
	v_mov_b32_e32 v40, 0

; __device__ void attn_item(const Params& p, char* lds, int bh, int qi) {
;     ...
;   f32x16 O[2];
; #pragma unroll
;   for (int d = 0; d < 2; ++d)
; #pragma unroll
;     for (int r = 0; r < 16; ++r) O[d][r] = 0.f;
;   float mref = 0.f, lsum = 0.f;
;   bool first = true;
;   const int nsteps = (qi + 1) * 4;
;   const int skey = tid >> 3, sch = tid & 7;
;   u32x4 rk, rv;
;   auto gload = [&](int s) {
;     const int jb = qi - (s >> 2), sub = s & 3, key0 = jb * 256 + sub * 64;
;     rk = *(const u32x4*)(Kg + (size_t)(key0 + skey) * 64 + sch * 8);
;     rv = *(const u32x4*)(Vg + (size_t)skey * SEQ + key0 + sch * 8);
;   };
;   auto swrite = [&](int buf) {
;     *(u32x4*)(Ks + buf * 64 * LD + skey * LD + sch * 8) = rk;
;     u16* vd = Vs + buf * 64 * LD + skey * LD + 16 * (sch >> 1) + 4 * (sch & 1);
;     u32x2 a, b; a.x = rv.x; a.y = rv.y; b.x = rv.z; b.y = rv.w;
;     *(u32x2*)(vd) = a;
;     *(u32x2*)(vd + 8) = b;
;   };
;   gload(0); swrite(0);
;   __syncthreads();
.LBB0_414:
	s_lshl_b32 s5, s22, 18
	s_lshl_b32 s5, s5, 1
	s_add_u32 s18, s10, s5
	v_or_b32_e32 v2, s4, v240
	v_mov_b32_e32 v3, v95
	v_lshl_add_u64 v[18:19], v[96:97], 0, s[6:7]
	s_mov_b32 s5, s7
	s_addc_u32 s19, s11, 0
	v_lshlrev_b64 v[2:3], 7, v[2:3]
	v_mov_b32_e32 v107, v95
	v_lshl_add_u64 v[4:5], s[4:5], 1, v[18:19]
	v_lshl_add_u64 v[2:3], s[18:19], 0, v[2:3]
	v_lshl_add_u64 v[4:5], v[4:5], 0, v[106:107]
	v_lshl_add_u64 v[2:3], v[2:3], 0, v[106:107]
	v_mov_b32_e32 v16, v95
	v_mov_b32_e32 v17, v95
	v_mov_b32_e32 v2, v95
	v_mov_b32_e32 v3, v95
	v_mov_b32_e32 v4, v95
	v_mov_b32_e32 v5, v95
	v_mov_b32_e32 v6, v95
	v_mov_b32_e32 v7, v95
	v_mov_b32_e32 v8, v95
	v_mov_b32_e32 v9, v95
	v_mov_b32_e32 v10, v95
	v_mov_b32_e32 v11, v95
	v_mov_b32_e32 v12, v95
	v_mov_b32_e32 v13, v95
	v_mov_b32_e32 v14, v95
	v_mov_b32_e32 v15, v95
	v_lshl_add_u64 v[108:109], v[18:19], 0, v[106:107]
	v_mov_b64_e32 v[32:33], v[16:17]
	s_lshl_b32 s38, s37, 2
	v_add_u32_e32 v34, 0x4800, v117
	s_mov_b32 s6, 0
	s_mov_b64 s[14:15], -1
	v_mov_b32_e32 v126, 0
	s_mov_b32 s26, 0
	v_mov_b64_e32 v[30:31], v[14:15]
	v_mov_b64_e32 v[28:29], v[12:13]
	v_mov_b64_e32 v[26:27], v[10:11]
	v_mov_b64_e32 v[24:25], v[8:9]
	v_mov_b64_e32 v[22:23], v[6:7]
	v_mov_b64_e32 v[20:21], v[4:5]
	v_mov_b64_e32 v[18:19], v[2:3]
	s_add_i32 s38, s38, 4
	v_lshl_add_u64 v[110:111], s[18:19], 0, v[106:107]
	v_mov_b32_e32 v107, 0
	s_waitcnt vmcnt(1)
	ds_write2_b64 v34, v[86:87], v[88:89] offset1:2
	s_waitcnt vmcnt(0)
	ds_write_b128 v116, v[82:85]
	s_waitcnt lgkmcnt(0)
	s_barrier
